# seams 4 and 5 as barriers of the four workgroups of a row block when co-located (run-time check), otherwise the global barrier; rest as the best version
# speedup vs baseline: 1.0074x; 1.0074x over previous
; __device__ __forceinline__ unsigned xb_ld(unsigned* p)              { return __hip_atomic_load(p, __ATOMIC_RELAXED, __HIP_MEMORY_SCOPE_AGENT); }
; __device__ __forceinline__ unsigned xb_add(unsigned* p, unsigned v) { return __hip_atomic_fetch_add(p, v, __ATOMIC_RELAXED, __HIP_MEMORY_SCOPE_AGENT); }
; #define XB_SPIN(cond, bar) do { unsigned _sp = 0; while (cond) { __builtin_amdgcn_s_sleep(1); \
;     if ((++_sp & 255u) == 0u) { if (xb_ld(&(bar)[XB_TMO])) break; if (_sp > XB_SPIN_CAP) { atomicAdd(&(bar)[XB_TMO], 1u); break; } } } } while (0)
; #define SEAM(k) do { if (IN(k) && IN((k) + 1)) { xcd_barrier(bar); } } while (0)
; __device__ __forceinline__ void xcd_barrier(const XcdBarrier& b) {
;     asm volatile("s_waitcnt vmcnt(0)" ::: "memory");
;     __syncthreads();
;     if (threadIdx.x == 0) {
;         unsigned* bar = b.bar;
;         __builtin_amdgcn_s_waitcnt(0);
;         unsigned nloc = b.st[0], nx = b.st[1];
;         if (nloc == 0u) { xcd_barrier_complete(bar, b.x, nloc, nx); b.st[0] = nloc; b.st[1] = nx; }
;         const unsigned old = xb_add(&bar[XB_XSUB(b.x)], 1u);
;         const unsigned gen = old / nloc;
;         if (old + 1u == (gen + 1u) * nloc) {
;             __builtin_amdgcn_fence(__ATOMIC_RELEASE, "agent");
;             asm volatile("s_waitcnt vmcnt(0)" ::: "memory");
;             const unsigned og = xb_add(&bar[XB_TOP], 1u);
;             const unsigned tg = og / nx;
;             if (og + 1u == (tg + 1u) * nx) xb_add(&bar[XB_TOPGEN], 1u);
;             else XB_SPIN(xb_ld(&bar[XB_TOPGEN]) == tg, bar);
;             __builtin_amdgcn_fence(__ATOMIC_ACQUIRE, "agent");
;             xb_add(&bar[XB_XGEN(b.x)], 1u);
;             asm volatile("s_waitcnt vmcnt(0)" ::: "memory");
;         } else {
;             XB_SPIN(xb_ld(&bar[XB_XGEN(b.x)]) == gen, bar);
;             __builtin_amdgcn_fence(__ATOMIC_ACQUIRE, "agent");
;             asm volatile("s_waitcnt vmcnt(0)" ::: "memory");
;         }
; __global__ void __launch_bounds__(NTHREADS, 2) hybrid_fwd(Args args) {
;     ...
;     SEAM(4);
.LBB0_905:
	s_cmp_gt_i32 s75, 5
	s_cselect_b64 s[2:3], -1, 0
	s_and_b64 s[0:1], s[0:1], s[2:3]
	s_andn2_b64 vcc, exec, s[0:1]
	s_cbranch_vccnz .LBB0_959
	s_waitcnt vmcnt(0)
	s_waitcnt vmcnt(0) lgkmcnt(0)
	s_barrier
	s_mov_b64 s[0:1], exec
	v_readlane_b32 s4, v254, 9
	v_readlane_b32 s5, v254, 10
	s_and_b64 s[4:5], s[0:1], s[4:5]
	s_mov_b64 exec, s[4:5]
	s_cbranch_execz .LBB0_958
	s_cmp_eq_u32 s74, 4
	s_cbranch_scc1 .Lmy_fb_4_orig
	s_add_i32 s4, 0, 0x26700
	v_mov_b32_e32 v0, s4
	ds_read_b32 v9, v0 offset:8
	s_waitcnt lgkmcnt(0)
	v_readfirstlane_b32 s9, v9
	s_cmp_eq_u32 s9, 0
	s_cbranch_scc1 .Lmy_fb_4_glob
	s_and_b32 s4, s33, 63
	s_lshl_b32 s4, s4, 3
	s_addk_i32 s4, 0x3c00
	v_mov_b32_e32 v4, s4
	v_mov_b32_e32 v5, 1
	global_atomic_add v4, v5, s[72:73]
	buffer_inv sc1
	s_mov_b32 s11, 0
.Lmy_fb_4_qspin:
	global_load_dword v0, v4, s[72:73] sc1
	s_waitcnt vmcnt(0)
	v_readfirstlane_b32 s10, v0
	s_cmp_ge_u32 s10, 4
	s_cbranch_scc1 .LBB0_958
	s_sleep 1
	s_add_i32 s11, s11, 1
	s_cmp_lt_u32 s11, 0x40000
	s_cbranch_scc1 .Lmy_fb_4_qspin
	s_branch .LBB0_958
.Lmy_fb_4_glob:
	s_add_i32 s4, 0, 0x26700
	v_mov_b32_e32 v0, s4
	ds_read2_b32 v[2:3], v0 offset1:1
	s_lshl_b32 s4, s88, 8
	s_add_u32 s4, s72, s4
	s_addc_u32 s5, s73, 0
	v_mov_b32_e32 v4, 0x1000
	v_mov_b32_e32 v5, 1
	global_atomic_add v4, v4, v5, s[4:5] offset:1024 sc0
	s_sub_i32 s6, 5, s74
	s_waitcnt lgkmcnt(0)
	v_readfirstlane_b32 s7, v2
	v_readfirstlane_b32 s8, v3
	s_mul_i32 s7, s7, s6
	s_add_i32 s6, s6, -1
	s_mul_i32 s8, s8, s6
	s_add_i32 s8, s8, 1
	v_mov_b32_e32 v6, 0x2000
	s_waitcnt vmcnt(0)
	v_readfirstlane_b32 s10, v4
	s_add_i32 s10, s10, 1
	s_cmp_lg_u32 s10, s7
	s_cbranch_scc1 .Lmy_fb_4_wait
	buffer_wbl2 sc1
	s_mov_b64 s[10:11], exec
	s_mov_b64 exec, 0xffff
	v_mbcnt_lo_u32_b32 v7, -1, 0
	v_lshlrev_b32_e32 v7, 8, v7
	v_add_u32_e32 v7, 0x2400, v7
	v_mov_b32_e32 v8, 1
	s_waitcnt vmcnt(0)
	global_atomic_add v7, v8, s[72:73]
	s_mov_b64 exec, s[10:11]

; __device__ __forceinline__ unsigned xb_ld(unsigned* p)              { return __hip_atomic_load(p, __ATOMIC_RELAXED, __HIP_MEMORY_SCOPE_AGENT); }
; __device__ __forceinline__ unsigned xb_add(unsigned* p, unsigned v) { return __hip_atomic_fetch_add(p, v, __ATOMIC_RELAXED, __HIP_MEMORY_SCOPE_AGENT); }
; #define XB_SPIN(cond, bar) do { unsigned _sp = 0; while (cond) { __builtin_amdgcn_s_sleep(1); \
;     if ((++_sp & 255u) == 0u) { if (xb_ld(&(bar)[XB_TMO])) break; if (_sp > XB_SPIN_CAP) { atomicAdd(&(bar)[XB_TMO], 1u); break; } } } } while (0)
; #define SEAM(k) do { if (IN(k) && IN((k) + 1)) { xcd_barrier(bar); } } while (0)
; __device__ __forceinline__ void xcd_barrier(const XcdBarrier& b) {
;     asm volatile("s_waitcnt vmcnt(0)" ::: "memory");
;     __syncthreads();
;     if (threadIdx.x == 0) {
;         unsigned* bar = b.bar;
;         __builtin_amdgcn_s_waitcnt(0);
;         unsigned nloc = b.st[0], nx = b.st[1];
;         if (nloc == 0u) { xcd_barrier_complete(bar, b.x, nloc, nx); b.st[0] = nloc; b.st[1] = nx; }
;         const unsigned old = xb_add(&bar[XB_XSUB(b.x)], 1u);
;         const unsigned gen = old / nloc;
;         if (old + 1u == (gen + 1u) * nloc) {
;             __builtin_amdgcn_fence(__ATOMIC_RELEASE, "agent");
;             asm volatile("s_waitcnt vmcnt(0)" ::: "memory");
;             const unsigned og = xb_add(&bar[XB_TOP], 1u);
;             const unsigned tg = og / nx;
;             if (og + 1u == (tg + 1u) * nx) xb_add(&bar[XB_TOPGEN], 1u);
;             else XB_SPIN(xb_ld(&bar[XB_TOPGEN]) == tg, bar);
;             __builtin_amdgcn_fence(__ATOMIC_ACQUIRE, "agent");
;             xb_add(&bar[XB_XGEN(b.x)], 1u);
;             asm volatile("s_waitcnt vmcnt(0)" ::: "memory");
;         } else {
;             XB_SPIN(xb_ld(&bar[XB_XGEN(b.x)]) == gen, bar);
;             __builtin_amdgcn_fence(__ATOMIC_ACQUIRE, "agent");
;             asm volatile("s_waitcnt vmcnt(0)" ::: "memory");
;         }
; __global__ void __launch_bounds__(NTHREADS, 2) hybrid_fwd(Args args) {
;     ...
;     SEAM(5);
.LBB0_976:
	s_cmp_gt_i32 s75, 6
	s_cselect_b64 s[2:3], -1, 0
	s_and_b64 s[0:1], s[0:1], s[2:3]
	s_andn2_b64 vcc, exec, s[0:1]
	s_cbranch_vccnz .LBB0_1030
	s_waitcnt vmcnt(0)
	s_waitcnt vmcnt(0) lgkmcnt(0)
	s_barrier
	s_mov_b64 s[0:1], exec
	v_readlane_b32 s4, v254, 9
	v_readlane_b32 s5, v254, 10
	s_and_b64 s[4:5], s[0:1], s[4:5]
	s_mov_b64 exec, s[4:5]
	s_cbranch_execz .LBB0_1029
	s_cmp_eq_u32 s74, 5
	s_cbranch_scc1 .Lmy_fb_5_orig
	s_add_i32 s4, 0, 0x26700
	v_mov_b32_e32 v0, s4
	ds_read_b32 v9, v0 offset:8
	s_waitcnt lgkmcnt(0)
	v_readfirstlane_b32 s9, v9
	s_cmp_eq_u32 s9, 0
	s_cbranch_scc1 .Lmy_fb_5_glob
	s_and_b32 s4, s33, 63
	s_lshl_b32 s4, s4, 3
	s_addk_i32 s4, 0x3e00
	v_mov_b32_e32 v4, s4
	v_mov_b32_e32 v5, 1
	global_atomic_add v4, v5, s[72:73]
	buffer_inv sc1
	s_mov_b32 s11, 0

; __device__ __forceinline__ unsigned xb_ld(unsigned* p)              { return __hip_atomic_load(p, __ATOMIC_RELAXED, __HIP_MEMORY_SCOPE_AGENT); }
; __device__ __forceinline__ unsigned xb_add(unsigned* p, unsigned v) { return __hip_atomic_fetch_add(p, v, __ATOMIC_RELAXED, __HIP_MEMORY_SCOPE_AGENT); }
; #define XB_SPIN(cond, bar) do { unsigned _sp = 0; while (cond) { __builtin_amdgcn_s_sleep(1); \
;     if ((++_sp & 255u) == 0u) { if (xb_ld(&(bar)[XB_TMO])) break; if (_sp > XB_SPIN_CAP) { atomicAdd(&(bar)[XB_TMO], 1u); break; } } } } while (0)
; __device__ __forceinline__ void xcd_barrier(const XcdBarrier& b) {
;     asm volatile("s_waitcnt vmcnt(0)" ::: "memory");
;     __syncthreads();
;     if (threadIdx.x == 0) {
;         unsigned* bar = b.bar;
;         __builtin_amdgcn_s_waitcnt(0);
;         unsigned nloc = b.st[0], nx = b.st[1];
;         if (nloc == 0u) { xcd_barrier_complete(bar, b.x, nloc, nx); b.st[0] = nloc; b.st[1] = nx; }
;         const unsigned old = xb_add(&bar[XB_XSUB(b.x)], 1u);
;         const unsigned gen = old / nloc;
;         if (old + 1u == (gen + 1u) * nloc) {
;             __builtin_amdgcn_fence(__ATOMIC_RELEASE, "agent");
;             asm volatile("s_waitcnt vmcnt(0)" ::: "memory");
;             const unsigned og = xb_add(&bar[XB_TOP], 1u);
;             const unsigned tg = og / nx;
;             if (og + 1u == (tg + 1u) * nx) xb_add(&bar[XB_TOPGEN], 1u);
;             else XB_SPIN(xb_ld(&bar[XB_TOPGEN]) == tg, bar);
;             __builtin_amdgcn_fence(__ATOMIC_ACQUIRE, "agent");
;             xb_add(&bar[XB_XGEN(b.x)], 1u);
;             asm volatile("s_waitcnt vmcnt(0)" ::: "memory");
;         } else {
;             XB_SPIN(xb_ld(&bar[XB_XGEN(b.x)]) == gen, bar);
;             __builtin_amdgcn_fence(__ATOMIC_ACQUIRE, "agent");
;             asm volatile("s_waitcnt vmcnt(0)" ::: "memory");
;         }
.Lmy_fb_5_glob:
	s_add_i32 s4, 0, 0x26700
	v_mov_b32_e32 v0, s4
	ds_read2_b32 v[2:3], v0 offset1:1
	s_lshl_b32 s4, s88, 8
	s_add_u32 s4, s72, s4
	s_addc_u32 s5, s73, 0
	v_mov_b32_e32 v4, 0x1000
	v_mov_b32_e32 v5, 1
	global_atomic_add v4, v4, v5, s[4:5] offset:1024 sc0
	s_sub_i32 s6, 6, s74
	s_waitcnt lgkmcnt(0)
	v_readfirstlane_b32 s7, v2
	v_readfirstlane_b32 s8, v3
	s_mul_i32 s7, s7, s6
	s_add_i32 s6, s6, -1
	s_mul_i32 s8, s8, s6
	s_add_i32 s8, s8, 1
	v_mov_b32_e32 v6, 0x2000
	s_waitcnt vmcnt(0)
	v_readfirstlane_b32 s10, v4
	s_add_i32 s10, s10, 1
	s_cmp_lg_u32 s10, s7
	s_cbranch_scc1 .Lmy_fb_5_wait
	buffer_wbl2 sc1
	s_mov_b64 s[10:11], exec
	s_mov_b64 exec, 0xffff
	v_mbcnt_lo_u32_b32 v7, -1, 0
	v_lshlrev_b32_e32 v7, 8, v7
	v_add_u32_e32 v7, 0x2400, v7
	v_mov_b32_e32 v8, 1
	s_waitcnt vmcnt(0)
	global_atomic_add v7, v8, s[72:73]
	s_mov_b64 exec, s[10:11]
